# the four GEMM K-loop heads aligned to 64 bytes (my earlier edits had shifted them to 4 mod 8; the baseline's gate/up loop sits on a 64-byte boundary)
# speedup vs baseline: 1.0051x; 1.0051x over previous
.LBB0_135:
	s_ashr_i32 s17, s16, 31
	s_lshl_b64 s[18:19], s[16:17], 20
	s_add_u32 s18, s28, s18
	s_addc_u32 s19, s29, s19
	s_and_b64 s[20:21], s[4:5], exec
	s_cselect_b32 s17, s19, s23
	s_cselect_b32 s44, s18, s22
	s_ashr_i32 s15, s14, 31
	s_lshl_b64 s[20:21], s[14:15], 20
	s_add_u32 s20, s30, s20
	s_addc_u32 s21, s31, s21
	s_and_b64 s[26:27], s[4:5], exec
	s_cselect_b32 s15, s21, s25
	s_cselect_b32 s45, s20, s24
	s_add_u32 s22, s22, 0x80080
	s_addc_u32 s23, s23, 0
	s_add_u32 s50, s24, 0x100
	v_mov_b32_e32 v0, 0
	s_addc_u32 s51, s25, 0
	s_mov_b32 s52, -2
	v_mov_b32_e32 v1, v0
	v_mov_b32_e32 v2, v0
	v_mov_b32_e32 v3, v0
	v_mov_b32_e32 v8, v0
	v_mov_b32_e32 v9, v0
	v_mov_b32_e32 v10, v0
	v_mov_b32_e32 v11, v0
	v_mov_b32_e32 v16, v0
	v_mov_b32_e32 v17, v0
	v_mov_b32_e32 v18, v0
	v_mov_b32_e32 v19, v0
	v_mov_b32_e32 v24, v0
	v_mov_b32_e32 v25, v0
	v_mov_b32_e32 v26, v0
	v_mov_b32_e32 v27, v0
	v_mov_b32_e32 v32, v0
	v_mov_b32_e32 v33, v0
	v_mov_b32_e32 v34, v0
	v_mov_b32_e32 v35, v0
	v_mov_b32_e32 v40, v0
	v_mov_b32_e32 v41, v0
	v_mov_b32_e32 v42, v0
	v_mov_b32_e32 v43, v0
	v_mov_b32_e32 v48, v0
	v_mov_b32_e32 v49, v0
	v_mov_b32_e32 v50, v0
	v_mov_b32_e32 v51, v0
	v_mov_b32_e32 v56, v0
	v_mov_b32_e32 v57, v0
	v_mov_b32_e32 v58, v0
	v_mov_b32_e32 v59, v0
	v_mov_b32_e32 v4, v0
	v_mov_b32_e32 v5, v0
	v_mov_b32_e32 v6, v0
	v_mov_b32_e32 v7, v0
	v_mov_b32_e32 v12, v0
	v_mov_b32_e32 v13, v0
	v_mov_b32_e32 v14, v0
	v_mov_b32_e32 v15, v0
	v_mov_b32_e32 v20, v0
	v_mov_b32_e32 v21, v0
	v_mov_b32_e32 v22, v0
	v_mov_b32_e32 v23, v0
	v_mov_b32_e32 v28, v0
	v_mov_b32_e32 v29, v0
	v_mov_b32_e32 v30, v0
	v_mov_b32_e32 v31, v0
	v_mov_b32_e32 v36, v0
	v_mov_b32_e32 v37, v0
	v_mov_b32_e32 v38, v0
	v_mov_b32_e32 v39, v0
	v_mov_b32_e32 v44, v0
	v_mov_b32_e32 v45, v0
	v_mov_b32_e32 v46, v0
	v_mov_b32_e32 v47, v0
	v_mov_b32_e32 v52, v0
	v_mov_b32_e32 v53, v0
	v_mov_b32_e32 v54, v0
	v_mov_b32_e32 v55, v0
	v_mov_b32_e32 v60, v0
	v_mov_b32_e32 v61, v0
	v_mov_b32_e32 v62, v0
	v_mov_b32_e32 v63, v0
	v_mov_b32_e32 v64, v0
	v_mov_b32_e32 v65, v0
	v_mov_b32_e32 v66, v0
	v_mov_b32_e32 v67, v0
	v_mov_b32_e32 v72, v0
	v_mov_b32_e32 v73, v0
	v_mov_b32_e32 v74, v0
	v_mov_b32_e32 v75, v0
	v_mov_b32_e32 v80, v0
	v_mov_b32_e32 v81, v0
	v_mov_b32_e32 v82, v0
	v_mov_b32_e32 v83, v0
	v_mov_b32_e32 v88, v0
	v_mov_b32_e32 v89, v0
	v_mov_b32_e32 v90, v0
	v_mov_b32_e32 v91, v0
	v_mov_b32_e32 v96, v0
	v_mov_b32_e32 v97, v0
	v_mov_b32_e32 v98, v0
	v_mov_b32_e32 v99, v0
	v_mov_b32_e32 v104, v0
	v_mov_b32_e32 v105, v0
	v_mov_b32_e32 v106, v0
	v_mov_b32_e32 v107, v0
	v_mov_b32_e32 v112, v0
	v_mov_b32_e32 v113, v0
	v_mov_b32_e32 v114, v0
	v_mov_b32_e32 v115, v0
	v_mov_b32_e32 v120, v0
	v_mov_b32_e32 v121, v0
	v_mov_b32_e32 v122, v0
	v_mov_b32_e32 v123, v0
	v_mov_b32_e32 v68, v0
	v_mov_b32_e32 v69, v0
	v_mov_b32_e32 v70, v0
	v_mov_b32_e32 v71, v0
	v_mov_b32_e32 v76, v0
	v_mov_b32_e32 v77, v0
	v_mov_b32_e32 v78, v0
	v_mov_b32_e32 v79, v0
	v_mov_b32_e32 v84, v0
	v_mov_b32_e32 v85, v0
	v_mov_b32_e32 v86, v0
	v_mov_b32_e32 v87, v0
	v_mov_b32_e32 v92, v0
	v_mov_b32_e32 v93, v0
	v_mov_b32_e32 v94, v0
	v_mov_b32_e32 v95, v0
	v_mov_b32_e32 v100, v0
	v_mov_b32_e32 v101, v0
	v_mov_b32_e32 v102, v0
	v_mov_b32_e32 v103, v0
	v_mov_b32_e32 v108, v0
	v_mov_b32_e32 v109, v0
	v_mov_b32_e32 v110, v0
	v_mov_b32_e32 v111, v0
	v_mov_b32_e32 v116, v0
	v_mov_b32_e32 v117, v0
	v_mov_b32_e32 v118, v0
	v_mov_b32_e32 v119, v0
	v_mov_b32_e32 v124, v0
	v_mov_b32_e32 v125, v0
	v_mov_b32_e32 v126, v0
	v_mov_b32_e32 v127, v0
	.p2align 6

.LBB0_212:
	s_add_u32 s52, s26, 0x100
	v_mov_b32_e32 v0, 0
	s_addc_u32 s53, s27, 0
	s_mov_b32 s56, -2
	v_mov_b32_e32 v1, v0
	v_mov_b32_e32 v2, v0
	v_mov_b32_e32 v3, v0
	v_mov_b32_e32 v4, v0
	v_mov_b32_e32 v5, v0
	v_mov_b32_e32 v6, v0
	v_mov_b32_e32 v7, v0
	v_mov_b32_e32 v8, v0
	v_mov_b32_e32 v9, v0
	v_mov_b32_e32 v10, v0
	v_mov_b32_e32 v11, v0
	v_mov_b32_e32 v16, v0
	v_mov_b32_e32 v17, v0
	v_mov_b32_e32 v18, v0
	v_mov_b32_e32 v19, v0
	v_mov_b32_e32 v24, v0
	v_mov_b32_e32 v25, v0
	v_mov_b32_e32 v26, v0
	v_mov_b32_e32 v27, v0
	v_mov_b32_e32 v32, v0
	v_mov_b32_e32 v33, v0
	v_mov_b32_e32 v34, v0
	v_mov_b32_e32 v35, v0
	v_mov_b32_e32 v40, v0
	v_mov_b32_e32 v41, v0
	v_mov_b32_e32 v42, v0
	v_mov_b32_e32 v43, v0
	v_mov_b32_e32 v48, v0
	v_mov_b32_e32 v49, v0
	v_mov_b32_e32 v50, v0
	v_mov_b32_e32 v51, v0
	v_mov_b32_e32 v12, v0
	v_mov_b32_e32 v13, v0
	v_mov_b32_e32 v14, v0
	v_mov_b32_e32 v15, v0
	v_mov_b32_e32 v20, v0
	v_mov_b32_e32 v21, v0
	v_mov_b32_e32 v22, v0
	v_mov_b32_e32 v23, v0
	v_mov_b32_e32 v28, v0
	v_mov_b32_e32 v29, v0
	v_mov_b32_e32 v30, v0
	v_mov_b32_e32 v31, v0
	v_mov_b32_e32 v36, v0
	v_mov_b32_e32 v37, v0
	v_mov_b32_e32 v38, v0
	v_mov_b32_e32 v39, v0
	v_mov_b32_e32 v44, v0
	v_mov_b32_e32 v45, v0
	v_mov_b32_e32 v46, v0
	v_mov_b32_e32 v47, v0
	v_mov_b32_e32 v52, v0
	v_mov_b32_e32 v53, v0
	v_mov_b32_e32 v54, v0
	v_mov_b32_e32 v55, v0
	v_mov_b32_e32 v56, v0
	v_mov_b32_e32 v57, v0
	v_mov_b32_e32 v58, v0
	v_mov_b32_e32 v59, v0
	v_mov_b32_e32 v60, v0
	v_mov_b32_e32 v61, v0
	v_mov_b32_e32 v62, v0
	v_mov_b32_e32 v63, v0
	v_mov_b32_e32 v64, v0
	v_mov_b32_e32 v65, v0
	v_mov_b32_e32 v66, v0
	v_mov_b32_e32 v67, v0
	v_mov_b32_e32 v68, v0
	v_mov_b32_e32 v69, v0
	v_mov_b32_e32 v70, v0
	v_mov_b32_e32 v71, v0
	v_mov_b32_e32 v72, v0
	v_mov_b32_e32 v73, v0
	v_mov_b32_e32 v74, v0
	v_mov_b32_e32 v75, v0
	v_mov_b32_e32 v80, v0
	v_mov_b32_e32 v81, v0
	v_mov_b32_e32 v82, v0
	v_mov_b32_e32 v83, v0
	v_mov_b32_e32 v88, v0
	v_mov_b32_e32 v89, v0
	v_mov_b32_e32 v90, v0
	v_mov_b32_e32 v91, v0
	v_mov_b32_e32 v96, v0
	v_mov_b32_e32 v97, v0
	v_mov_b32_e32 v98, v0
	v_mov_b32_e32 v99, v0
	v_mov_b32_e32 v104, v0
	v_mov_b32_e32 v105, v0
	v_mov_b32_e32 v106, v0
	v_mov_b32_e32 v107, v0
	v_mov_b32_e32 v112, v0
	v_mov_b32_e32 v113, v0
	v_mov_b32_e32 v114, v0
	v_mov_b32_e32 v115, v0
	v_mov_b32_e32 v76, v0
	v_mov_b32_e32 v77, v0
	v_mov_b32_e32 v78, v0
	v_mov_b32_e32 v79, v0
	v_mov_b32_e32 v84, v0
	v_mov_b32_e32 v85, v0
	v_mov_b32_e32 v86, v0
	v_mov_b32_e32 v87, v0
	v_mov_b32_e32 v92, v0
	v_mov_b32_e32 v93, v0
	v_mov_b32_e32 v94, v0
	v_mov_b32_e32 v95, v0
	v_mov_b32_e32 v100, v0
	v_mov_b32_e32 v101, v0
	v_mov_b32_e32 v102, v0
	v_mov_b32_e32 v103, v0
	v_mov_b32_e32 v108, v0
	v_mov_b32_e32 v109, v0
	v_mov_b32_e32 v110, v0
	v_mov_b32_e32 v111, v0
	v_mov_b32_e32 v116, v0
	v_mov_b32_e32 v117, v0
	v_mov_b32_e32 v118, v0
	v_mov_b32_e32 v119, v0
	v_mov_b32_e32 v120, v0
	v_mov_b32_e32 v121, v0
	v_mov_b32_e32 v122, v0
	v_mov_b32_e32 v123, v0
	v_mov_b32_e32 v124, v0
	v_mov_b32_e32 v125, v0
	v_mov_b32_e32 v126, v0
	v_mov_b32_e32 v127, v0
	.p2align 6

.LBB0_354:
	s_ashr_i32 s17, s16, 31
	s_lshl_b64 s[18:19], s[16:17], 20
	s_add_u32 s18, s4, s18
	s_addc_u32 s19, s5, s19
	s_and_b64 s[20:21], s[6:7], exec
	s_cselect_b32 s17, s19, s23
	s_cselect_b32 s42, s18, s22
	s_ashr_i32 s15, s14, 31
	s_lshl_b64 s[20:21], s[14:15], 20
	s_add_u32 s20, s28, s20
	s_addc_u32 s21, s29, s21
	s_and_b64 s[26:27], s[6:7], exec
	s_cselect_b32 s15, s21, s25
	s_cselect_b32 s43, s20, s24
	s_add_u32 s22, s22, 0x80080
	s_addc_u32 s23, s23, 0
	s_add_u32 s44, s24, 0x100
	v_mov_b32_e32 v0, 0
	s_addc_u32 s45, s25, 0
	s_mov_b32 s50, -2
	v_mov_b32_e32 v1, v0
	v_mov_b32_e32 v2, v0
	v_mov_b32_e32 v3, v0
	v_mov_b32_e32 v4, v0
	v_mov_b32_e32 v5, v0
	v_mov_b32_e32 v6, v0
	v_mov_b32_e32 v7, v0
	v_mov_b32_e32 v8, v0
	v_mov_b32_e32 v9, v0
	v_mov_b32_e32 v10, v0
	v_mov_b32_e32 v11, v0
	v_mov_b32_e32 v16, v0
	v_mov_b32_e32 v17, v0
	v_mov_b32_e32 v18, v0
	v_mov_b32_e32 v19, v0
	v_mov_b32_e32 v24, v0
	v_mov_b32_e32 v25, v0
	v_mov_b32_e32 v26, v0
	v_mov_b32_e32 v27, v0
	v_mov_b32_e32 v32, v0
	v_mov_b32_e32 v33, v0
	v_mov_b32_e32 v34, v0
	v_mov_b32_e32 v35, v0
	v_mov_b32_e32 v40, v0
	v_mov_b32_e32 v41, v0
	v_mov_b32_e32 v42, v0
	v_mov_b32_e32 v43, v0
	v_mov_b32_e32 v48, v0
	v_mov_b32_e32 v49, v0
	v_mov_b32_e32 v50, v0
	v_mov_b32_e32 v51, v0
	v_mov_b32_e32 v12, v0
	v_mov_b32_e32 v13, v0
	v_mov_b32_e32 v14, v0
	v_mov_b32_e32 v15, v0
	v_mov_b32_e32 v20, v0
	v_mov_b32_e32 v21, v0
	v_mov_b32_e32 v22, v0
	v_mov_b32_e32 v23, v0
	v_mov_b32_e32 v28, v0
	v_mov_b32_e32 v29, v0
	v_mov_b32_e32 v30, v0
	v_mov_b32_e32 v31, v0
	v_mov_b32_e32 v36, v0
	v_mov_b32_e32 v37, v0
	v_mov_b32_e32 v38, v0
	v_mov_b32_e32 v39, v0
	v_mov_b32_e32 v44, v0
	v_mov_b32_e32 v45, v0
	v_mov_b32_e32 v46, v0
	v_mov_b32_e32 v47, v0
	v_mov_b32_e32 v52, v0
	v_mov_b32_e32 v53, v0
	v_mov_b32_e32 v54, v0
	v_mov_b32_e32 v55, v0
	v_mov_b32_e32 v56, v0
	v_mov_b32_e32 v57, v0
	v_mov_b32_e32 v58, v0
	v_mov_b32_e32 v59, v0
	v_mov_b32_e32 v60, v0
	v_mov_b32_e32 v61, v0
	v_mov_b32_e32 v62, v0
	v_mov_b32_e32 v63, v0
	v_mov_b32_e32 v64, v0
	v_mov_b32_e32 v65, v0
	v_mov_b32_e32 v66, v0
	v_mov_b32_e32 v67, v0
	v_mov_b32_e32 v68, v0
	v_mov_b32_e32 v69, v0
	v_mov_b32_e32 v70, v0
	v_mov_b32_e32 v71, v0
	v_mov_b32_e32 v72, v0
	v_mov_b32_e32 v73, v0
	v_mov_b32_e32 v74, v0
	v_mov_b32_e32 v75, v0
	v_mov_b32_e32 v80, v0
	v_mov_b32_e32 v81, v0
	v_mov_b32_e32 v82, v0
	v_mov_b32_e32 v83, v0
	v_mov_b32_e32 v88, v0
	v_mov_b32_e32 v89, v0
	v_mov_b32_e32 v90, v0
	v_mov_b32_e32 v91, v0
	v_mov_b32_e32 v96, v0
	v_mov_b32_e32 v97, v0
	v_mov_b32_e32 v98, v0
	v_mov_b32_e32 v99, v0
	v_mov_b32_e32 v104, v0
	v_mov_b32_e32 v105, v0
	v_mov_b32_e32 v106, v0
	v_mov_b32_e32 v107, v0
	v_mov_b32_e32 v112, v0
	v_mov_b32_e32 v113, v0
	v_mov_b32_e32 v114, v0
	v_mov_b32_e32 v115, v0
	v_mov_b32_e32 v76, v0
	v_mov_b32_e32 v77, v0
	v_mov_b32_e32 v78, v0
	v_mov_b32_e32 v79, v0
	v_mov_b32_e32 v84, v0
	v_mov_b32_e32 v85, v0
	v_mov_b32_e32 v86, v0
	v_mov_b32_e32 v87, v0
	v_mov_b32_e32 v92, v0
	v_mov_b32_e32 v93, v0
	v_mov_b32_e32 v94, v0
	v_mov_b32_e32 v95, v0
	v_mov_b32_e32 v100, v0
	v_mov_b32_e32 v101, v0
	v_mov_b32_e32 v102, v0
	v_mov_b32_e32 v103, v0
	v_mov_b32_e32 v108, v0
	v_mov_b32_e32 v109, v0
	v_mov_b32_e32 v110, v0
	v_mov_b32_e32 v111, v0
	v_mov_b32_e32 v116, v0
	v_mov_b32_e32 v117, v0
	v_mov_b32_e32 v118, v0
	v_mov_b32_e32 v119, v0
	v_mov_b32_e32 v120, v0
	v_mov_b32_e32 v121, v0
	v_mov_b32_e32 v122, v0
	v_mov_b32_e32 v123, v0
	v_mov_b32_e32 v124, v0
	v_mov_b32_e32 v125, v0
	v_mov_b32_e32 v126, v0
	v_mov_b32_e32 v127, v0
	.p2align 6

.LBB0_683:
	s_ashr_i32 s15, s14, 31
	s_lshl_b64 s[16:17], s[14:15], 20
	s_add_u32 s16, s26, s16
	s_addc_u32 s17, s27, s17
	s_and_b64 s[18:19], s[4:5], exec
	s_cselect_b32 s15, s17, s21
	s_cselect_b32 s42, s16, s20
	s_ashr_i32 s13, s12, 31
	s_lshl_b64 s[18:19], s[12:13], 20
	s_add_u32 s18, s28, s18
	s_addc_u32 s19, s29, s19
	s_and_b64 s[24:25], s[4:5], exec
	s_cselect_b32 s13, s19, s23
	s_cselect_b32 s43, s18, s22
	s_add_u32 s20, s20, 0x80080
	s_addc_u32 s21, s21, 0
	s_add_u32 s44, s22, 0x100
	v_mov_b32_e32 v0, 0
	s_addc_u32 s45, s23, 0
	s_mov_b32 s50, -2
	v_mov_b32_e32 v1, v0
	v_mov_b32_e32 v2, v0
	v_mov_b32_e32 v3, v0
	v_mov_b32_e32 v4, v0
	v_mov_b32_e32 v5, v0
	v_mov_b32_e32 v6, v0
	v_mov_b32_e32 v7, v0
	v_mov_b32_e32 v8, v0
	v_mov_b32_e32 v9, v0
	v_mov_b32_e32 v10, v0
	v_mov_b32_e32 v11, v0
	v_mov_b32_e32 v16, v0
	v_mov_b32_e32 v17, v0
	v_mov_b32_e32 v18, v0
	v_mov_b32_e32 v19, v0
	v_mov_b32_e32 v24, v0
	v_mov_b32_e32 v25, v0
	v_mov_b32_e32 v26, v0
	v_mov_b32_e32 v27, v0
	v_mov_b32_e32 v32, v0
	v_mov_b32_e32 v33, v0
	v_mov_b32_e32 v34, v0
	v_mov_b32_e32 v35, v0
	v_mov_b32_e32 v40, v0
	v_mov_b32_e32 v41, v0
	v_mov_b32_e32 v42, v0
	v_mov_b32_e32 v43, v0
	v_mov_b32_e32 v48, v0
	v_mov_b32_e32 v49, v0
	v_mov_b32_e32 v50, v0
	v_mov_b32_e32 v51, v0
	v_mov_b32_e32 v12, v0
	v_mov_b32_e32 v13, v0
	v_mov_b32_e32 v14, v0
	v_mov_b32_e32 v15, v0
	v_mov_b32_e32 v20, v0
	v_mov_b32_e32 v21, v0
	v_mov_b32_e32 v22, v0
	v_mov_b32_e32 v23, v0
	v_mov_b32_e32 v28, v0
	v_mov_b32_e32 v29, v0
	v_mov_b32_e32 v30, v0
	v_mov_b32_e32 v31, v0
	v_mov_b32_e32 v36, v0
	v_mov_b32_e32 v37, v0
	v_mov_b32_e32 v38, v0
	v_mov_b32_e32 v39, v0
	v_mov_b32_e32 v44, v0
	v_mov_b32_e32 v45, v0
	v_mov_b32_e32 v46, v0
	v_mov_b32_e32 v47, v0
	v_mov_b32_e32 v52, v0
	v_mov_b32_e32 v53, v0
	v_mov_b32_e32 v54, v0
	v_mov_b32_e32 v55, v0
	v_mov_b32_e32 v56, v0
	v_mov_b32_e32 v57, v0
	v_mov_b32_e32 v58, v0
	v_mov_b32_e32 v59, v0
	v_mov_b32_e32 v60, v0
	v_mov_b32_e32 v61, v0
	v_mov_b32_e32 v62, v0
	v_mov_b32_e32 v63, v0
	v_mov_b32_e32 v64, v0
	v_mov_b32_e32 v65, v0
	v_mov_b32_e32 v66, v0
	v_mov_b32_e32 v67, v0
	v_mov_b32_e32 v68, v0
	v_mov_b32_e32 v69, v0
	v_mov_b32_e32 v70, v0
	v_mov_b32_e32 v71, v0
	v_mov_b32_e32 v72, v0
	v_mov_b32_e32 v73, v0
	v_mov_b32_e32 v74, v0
	v_mov_b32_e32 v75, v0
	v_mov_b32_e32 v80, v0
	v_mov_b32_e32 v81, v0
	v_mov_b32_e32 v82, v0
	v_mov_b32_e32 v83, v0
	v_mov_b32_e32 v88, v0
	v_mov_b32_e32 v89, v0
	v_mov_b32_e32 v90, v0
	v_mov_b32_e32 v91, v0
	v_mov_b32_e32 v96, v0
	v_mov_b32_e32 v97, v0
	v_mov_b32_e32 v98, v0
	v_mov_b32_e32 v99, v0
	v_mov_b32_e32 v104, v0
	v_mov_b32_e32 v105, v0
	v_mov_b32_e32 v106, v0
	v_mov_b32_e32 v107, v0
	v_mov_b32_e32 v112, v0
	v_mov_b32_e32 v113, v0
	v_mov_b32_e32 v114, v0
	v_mov_b32_e32 v115, v0
	v_mov_b32_e32 v76, v0
	v_mov_b32_e32 v77, v0
	v_mov_b32_e32 v78, v0
	v_mov_b32_e32 v79, v0
	v_mov_b32_e32 v84, v0
	v_mov_b32_e32 v85, v0
	v_mov_b32_e32 v86, v0
	v_mov_b32_e32 v87, v0
	v_mov_b32_e32 v92, v0
	v_mov_b32_e32 v93, v0
	v_mov_b32_e32 v94, v0
	v_mov_b32_e32 v95, v0
	v_mov_b32_e32 v100, v0
	v_mov_b32_e32 v101, v0
	v_mov_b32_e32 v102, v0
	v_mov_b32_e32 v103, v0
	v_mov_b32_e32 v108, v0
	v_mov_b32_e32 v109, v0
	v_mov_b32_e32 v110, v0
	v_mov_b32_e32 v111, v0
	v_mov_b32_e32 v116, v0
	v_mov_b32_e32 v117, v0
	v_mov_b32_e32 v118, v0
	v_mov_b32_e32 v119, v0
	v_mov_b32_e32 v120, v0
	v_mov_b32_e32 v121, v0
	v_mov_b32_e32 v122, v0
	v_mov_b32_e32 v123, v0
	v_mov_b32_e32 v124, v0
	v_mov_b32_e32 v125, v0
	v_mov_b32_e32 v126, v0
	v_mov_b32_e32 v127, v0
	.p2align 6
